# phase 0: transposes no longer drain stores before each tile barrier; lru_weight_job issues its 32 element loads together
# speedup vs baseline: 1.0006x; 1.0006x over previous
; __device__ __forceinline__ u16 f2bf(float f) { return (u16)(pack2(f, 0.f) & 0xffffu); }
; __device__ __forceinline__ int ltid() { int t = threadIdx.x; asm volatile("" : "+v"(t)); return t; }
; __device__ __forceinline__ void lru_weight_job(const P& p, int h) {
;   for (int e = ltid(); e < 128 * 64; e += 256) {
;     const int r = e >> 6, k = e & 63;
;     const int ch = (r >> 6) * 32 + ((r >> 5) & 1) * 16 + (r & 15);
;     const float* src = ((r >> 4) & 1) ? p.lw_x : p.lw_a;
;     p.Lwt[(size_t)(h * 128 + r) * 64 + k] = f2bf(src[h * 4096 + k * 64 + ch]);
;   }
; }
.LBB0_536:
	s_cmp_gt_i32 s34, 31
	s_mov_b64 s[6:7], -1
	s_cbranch_scc0 .LBB0_543
	s_cmp_gt_u32 s34, 39
	s_cbranch_scc1 .LBB0_542
	v_mov_b32_e32 v2, v132
	s_nop 0
	v_cmp_gt_i32_e32 vcc, s83, v2
	s_and_saveexec_b64 s[6:7], vcc
	s_cbranch_execz .LBB0_541
	s_sub_i32 s4, s34, 32
	s_load_dwordx2 s[10:11], s[0:1], 0x1e8
	s_load_dwordx2 s[12:13], s[0:1], 0x130
	s_load_dwordx2 s[14:15], s[0:1], 0x140
	s_lshl_b32 s8, s4, 14
	v_and_b32_e32 v0, 63, v132
	v_lshrrev_b32_e32 v1, 6, v132
	v_lshlrev_b32_e32 v10, 8, v0
	v_lshl_add_u32 v10, v1, 2, v10
	v_add_u32_e32 v10, s8, v10
	v_lshlrev_b32_e32 v11, 7, v1
	v_lshl_add_u32 v11, v0, 1, v11
	v_add_u32_e32 v11, s8, v11
	v_add_u32_e32 v12, 0x1000, v11
	v_add_u32_e32 v13, 0x2000, v11
	v_add_u32_e32 v14, 0x3000, v11
	s_waitcnt vmcnt(0) lgkmcnt(0)
	global_load_dword v16, v10, s[12:13] offset:0
	global_load_dword v17, v10, s[12:13] offset:16
	global_load_dword v18, v10, s[12:13] offset:32
	global_load_dword v19, v10, s[12:13] offset:48
	global_load_dword v20, v10, s[14:15] offset:0
	global_load_dword v21, v10, s[14:15] offset:16
	global_load_dword v22, v10, s[14:15] offset:32
	global_load_dword v23, v10, s[14:15] offset:48
	global_load_dword v24, v10, s[12:13] offset:64
	global_load_dword v25, v10, s[12:13] offset:80
	global_load_dword v26, v10, s[12:13] offset:96
	global_load_dword v27, v10, s[12:13] offset:112
	global_load_dword v28, v10, s[14:15] offset:64
	global_load_dword v29, v10, s[14:15] offset:80
	global_load_dword v30, v10, s[14:15] offset:96
	global_load_dword v31, v10, s[14:15] offset:112
	global_load_dword v32, v10, s[12:13] offset:128
	global_load_dword v33, v10, s[12:13] offset:144
	global_load_dword v34, v10, s[12:13] offset:160
	global_load_dword v35, v10, s[12:13] offset:176
	global_load_dword v36, v10, s[14:15] offset:128
	global_load_dword v37, v10, s[14:15] offset:144
	global_load_dword v38, v10, s[14:15] offset:160
	global_load_dword v39, v10, s[14:15] offset:176
	global_load_dword v40, v10, s[12:13] offset:192
	global_load_dword v41, v10, s[12:13] offset:208
	global_load_dword v42, v10, s[12:13] offset:224
	global_load_dword v43, v10, s[12:13] offset:240
	global_load_dword v44, v10, s[14:15] offset:192
	global_load_dword v45, v10, s[14:15] offset:208
	global_load_dword v46, v10, s[14:15] offset:224
	global_load_dword v47, v10, s[14:15] offset:240
	s_waitcnt vmcnt(31)
	v_cvt_pk_bf16_f32 v16, v16, v16
	s_waitcnt vmcnt(30)
	v_cvt_pk_bf16_f32 v17, v17, v17
	s_waitcnt vmcnt(29)
	v_cvt_pk_bf16_f32 v18, v18, v18
	s_waitcnt vmcnt(28)
	v_cvt_pk_bf16_f32 v19, v19, v19
	s_waitcnt vmcnt(27)
	v_cvt_pk_bf16_f32 v20, v20, v20
	s_waitcnt vmcnt(26)
	v_cvt_pk_bf16_f32 v21, v21, v21
	s_waitcnt vmcnt(25)
	v_cvt_pk_bf16_f32 v22, v22, v22
	s_waitcnt vmcnt(24)
	v_cvt_pk_bf16_f32 v23, v23, v23
	s_waitcnt vmcnt(23)
	v_cvt_pk_bf16_f32 v24, v24, v24
	s_waitcnt vmcnt(22)
	v_cvt_pk_bf16_f32 v25, v25, v25
	s_waitcnt vmcnt(21)
	v_cvt_pk_bf16_f32 v26, v26, v26
	s_waitcnt vmcnt(20)
	v_cvt_pk_bf16_f32 v27, v27, v27
	s_waitcnt vmcnt(19)
	v_cvt_pk_bf16_f32 v28, v28, v28
	s_waitcnt vmcnt(18)
	v_cvt_pk_bf16_f32 v29, v29, v29
	s_waitcnt vmcnt(17)
	v_cvt_pk_bf16_f32 v30, v30, v30
	s_waitcnt vmcnt(16)
	v_cvt_pk_bf16_f32 v31, v31, v31
	s_waitcnt vmcnt(15)
	v_cvt_pk_bf16_f32 v32, v32, v32
	s_waitcnt vmcnt(14)
	v_cvt_pk_bf16_f32 v33, v33, v33
	s_waitcnt vmcnt(13)
	v_cvt_pk_bf16_f32 v34, v34, v34
	s_waitcnt vmcnt(12)
	v_cvt_pk_bf16_f32 v35, v35, v35
	s_waitcnt vmcnt(11)
	v_cvt_pk_bf16_f32 v36, v36, v36
	s_waitcnt vmcnt(10)
	v_cvt_pk_bf16_f32 v37, v37, v37
	s_waitcnt vmcnt(9)
	v_cvt_pk_bf16_f32 v38, v38, v38
	s_waitcnt vmcnt(8)
	v_cvt_pk_bf16_f32 v39, v39, v39
	s_waitcnt vmcnt(7)
	v_cvt_pk_bf16_f32 v40, v40, v40
	s_waitcnt vmcnt(6)
	v_cvt_pk_bf16_f32 v41, v41, v41
	s_waitcnt vmcnt(5)
	v_cvt_pk_bf16_f32 v42, v42, v42
	s_waitcnt vmcnt(4)
	v_cvt_pk_bf16_f32 v43, v43, v43
	s_waitcnt vmcnt(3)
	v_cvt_pk_bf16_f32 v44, v44, v44
	s_waitcnt vmcnt(2)
	v_cvt_pk_bf16_f32 v45, v45, v45
	s_waitcnt vmcnt(1)
	v_cvt_pk_bf16_f32 v46, v46, v46
	s_waitcnt vmcnt(0)
	v_cvt_pk_bf16_f32 v47, v47, v47
	global_store_short v11, v16, s[10:11] offset:0
	global_store_short v11, v17, s[10:11] offset:512
	global_store_short v11, v18, s[10:11] offset:1024
	global_store_short v11, v19, s[10:11] offset:1536
	global_store_short v11, v20, s[10:11] offset:2048
	global_store_short v11, v21, s[10:11] offset:2560
	global_store_short v11, v22, s[10:11] offset:3072
	global_store_short v11, v23, s[10:11] offset:3584
	global_store_short v12, v24, s[10:11] offset:0
	global_store_short v12, v25, s[10:11] offset:512
	global_store_short v12, v26, s[10:11] offset:1024
	global_store_short v12, v27, s[10:11] offset:1536
	global_store_short v12, v28, s[10:11] offset:2048
	global_store_short v12, v29, s[10:11] offset:2560
	global_store_short v12, v30, s[10:11] offset:3072
	global_store_short v12, v31, s[10:11] offset:3584
	global_store_short v13, v32, s[10:11] offset:0
	global_store_short v13, v33, s[10:11] offset:512
	global_store_short v13, v34, s[10:11] offset:1024
	global_store_short v13, v35, s[10:11] offset:1536
	global_store_short v13, v36, s[10:11] offset:2048
	global_store_short v13, v37, s[10:11] offset:2560
	global_store_short v13, v38, s[10:11] offset:3072
	global_store_short v13, v39, s[10:11] offset:3584
	global_store_short v14, v40, s[10:11] offset:0
	global_store_short v14, v41, s[10:11] offset:512
	global_store_short v14, v42, s[10:11] offset:1024
	global_store_short v14, v43, s[10:11] offset:1536
	global_store_short v14, v44, s[10:11] offset:2048
	global_store_short v14, v45, s[10:11] offset:2560
	global_store_short v14, v46, s[10:11] offset:3072
	global_store_short v14, v47, s[10:11] offset:3584

; __device__ __forceinline__ int ltid() { int t = threadIdx.x; asm volatile("" : "+v"(t)); return t; }
; __device__ __forceinline__ void transpose_tile(const TDesc& d, int tile, float* sm) {
;   const int ktn = d.K >> 6;
;   const int kt = tile % ktn, ntl = tile / ktn;
;   const int k0 = kt * 64, n0 = ntl * 64;
;   const int tid = ltid();
;   __syncthreads();
; #pragma unroll
;   for (int i = 0; i < 16; i++) {
;     int e = tid + i * 256;
;     int kk = e >> 6, nn = e & 63;
;     const int nc = n0 + nn;
;     float v = __builtin_nontemporal_load(&d.src[(size_t)(k0 + kk) * d.N + (nc < d.N ? nc : d.N - 1)]);
;     sm[kk * 65 + nn] = (nc < d.N) ? v : 0.f;
;   }
;   __syncthreads();
; #pragma unroll
;   for (int i = 0; i < 2; i++) {
;     int e = tid + i * 256;
;     int nn = e >> 3, kc = (e & 7) * 8;
;     float f[8];
; #pragma unroll
;     for (int q = 0; q < 8; q++) f[q] = sm[(kc + q) * 65 + nn];
;     *(bf16x8*)(d.dst + (size_t)(n0 + nn) * d.K + k0 + kc) = pack8(f);
;   }
; }
; __device__ __forceinline__ void transpose_jobs(const TDesc* tab, int ntab, int ntiles, float* sm, int job0, int jstride) {
;   for (int t = job0; t < ntiles; t += jstride) {
;     int di = 0;
;     for (int i = 1; i < ntab; i++)
;       if (t >= tab[i].t0) di = i;
;     transpose_tile(tab[di], t - tab[di].t0, sm);
;   }
; }
.LBB0_599:
	s_lshl_b64 s[6:7], s[6:7], 5
	s_add_u32 s12, s0, s6
	s_addc_u32 s13, s1, s7
	s_load_dwordx4 s[8:11], s[12:13], 0x238
	s_load_dwordx2 s[6:7], s[12:13], 0x248
	s_load_dword s4, s[12:13], 0x254
	v_mov_b32_e32 v1, v132
	s_load_dword s12, s[12:13], 0x248
	s_waitcnt lgkmcnt(0)
	v_mov_b32_e32 v2, s8
	s_sub_i32 s4, s14, s4
	s_abs_i32 s15, s4
	s_ashr_i32 s12, s12, 6
	s_abs_i32 s16, s12
	v_cvt_f32_u32_e32 v0, s16
	s_sub_i32 s17, 0, s16
	s_xor_b32 s13, s4, s12
	s_ashr_i32 s13, s13, 31
	v_rcp_iflag_f32_e32 v0, v0
	v_mov_b32_e32 v3, s9
	v_ashrrev_i32_e32 v6, 6, v1
	s_nop 0
	v_mul_f32_e32 v0, 0x4f7ffffe, v0
	v_cvt_u32_f32_e32 v0, v0
	s_barrier
	v_ashrrev_i32_e32 v11, 3, v1
	v_readfirstlane_b32 s34, v0
	s_mul_i32 s17, s17, s34
	s_mul_hi_u32 s17, s34, s17
	s_add_i32 s34, s34, s17
	s_mul_hi_u32 s17, s15, s34
	s_mul_i32 s34, s17, s16
	s_sub_i32 s15, s15, s34
	s_add_i32 s34, s17, 1
	s_sub_i32 s35, s15, s16
	s_cmp_ge_u32 s15, s16
	s_cselect_b32 s17, s34, s17
	s_cselect_b32 s15, s35, s15
	s_add_i32 s34, s17, 1
	s_cmp_ge_u32 s15, s16
	s_cselect_b32 s15, s34, s17
	s_xor_b32 s15, s15, s13
	s_sub_i32 s13, s15, s13
	s_mul_i32 s12, s13, s12
	s_sub_i32 s4, s4, s12
	s_lshl_b32 s12, s4, 6
	s_lshl_b32 s4, s13, 6
	v_and_b32_e32 v0, 63, v1
	v_or_b32_e32 v4, s4, v0
	s_add_i32 s8, s7, -1
	v_cmp_gt_i32_e32 vcc, s7, v4
	v_min_i32_e32 v4, s8, v4
	v_ashrrev_i32_e32 v5, 31, v4
	v_lshl_add_u64 v[2:3], v[4:5], 2, v[2:3]
	v_add_u32_e32 v4, s12, v6
	v_mad_i64_i32 v[4:5], s[8:9], s7, v4, 0
	v_lshl_add_u64 v[4:5], v[4:5], 2, v[2:3]
	v_lshlrev_b32_e32 v0, 2, v0
	s_ashr_i32 s13, s12, 31
	v_readlane_b32 s34, v229, 5
	v_readlane_b32 s35, v229, 6
	v_mov_b32_e32 v28, s7
	v_mov_b32_e32 v29, 0
	v_lshlrev_b32_e32 v28, 4, v28
	v_mad_u32_u24 v30, v6, s77, v0
	global_load_dword v12, v[4:5], off nt
	v_lshl_add_u64 v[4:5], v[4:5], 0, v[28:29]
	global_load_dword v13, v[4:5], off nt
	v_lshl_add_u64 v[4:5], v[4:5], 0, v[28:29]
	global_load_dword v14, v[4:5], off nt
	v_lshl_add_u64 v[4:5], v[4:5], 0, v[28:29]
	global_load_dword v15, v[4:5], off nt
	v_lshl_add_u64 v[4:5], v[4:5], 0, v[28:29]
	global_load_dword v16, v[4:5], off nt
	v_lshl_add_u64 v[4:5], v[4:5], 0, v[28:29]
	global_load_dword v17, v[4:5], off nt
	v_lshl_add_u64 v[4:5], v[4:5], 0, v[28:29]
	global_load_dword v18, v[4:5], off nt
	v_lshl_add_u64 v[4:5], v[4:5], 0, v[28:29]
	global_load_dword v19, v[4:5], off nt
	v_lshl_add_u64 v[4:5], v[4:5], 0, v[28:29]
	global_load_dword v20, v[4:5], off nt
	v_lshl_add_u64 v[4:5], v[4:5], 0, v[28:29]
	global_load_dword v21, v[4:5], off nt
	v_lshl_add_u64 v[4:5], v[4:5], 0, v[28:29]
	global_load_dword v22, v[4:5], off nt
	v_lshl_add_u64 v[4:5], v[4:5], 0, v[28:29]
	global_load_dword v23, v[4:5], off nt
	v_lshl_add_u64 v[4:5], v[4:5], 0, v[28:29]
	global_load_dword v24, v[4:5], off nt
	v_lshl_add_u64 v[4:5], v[4:5], 0, v[28:29]
	global_load_dword v25, v[4:5], off nt
	v_lshl_add_u64 v[4:5], v[4:5], 0, v[28:29]
	global_load_dword v26, v[4:5], off nt
	v_lshl_add_u64 v[4:5], v[4:5], 0, v[28:29]
	global_load_dword v27, v[4:5], off nt
	s_waitcnt vmcnt(15)
	v_cndmask_b32_e32 v31, 0, v12, vcc
	ds_write_b32 v30, v31
	s_waitcnt vmcnt(14)
	v_cndmask_b32_e32 v32, 0, v13, vcc
	ds_write_b32 v30, v32 offset:1040
	s_waitcnt vmcnt(13)
	v_cndmask_b32_e32 v31, 0, v14, vcc
	ds_write_b32 v30, v31 offset:2080
	s_waitcnt vmcnt(12)
	v_cndmask_b32_e32 v32, 0, v15, vcc
	ds_write_b32 v30, v32 offset:3120
	s_waitcnt vmcnt(11)
	v_cndmask_b32_e32 v31, 0, v16, vcc
	ds_write_b32 v30, v31 offset:4160
	s_waitcnt vmcnt(10)
	v_cndmask_b32_e32 v32, 0, v17, vcc
	ds_write_b32 v30, v32 offset:5200
	s_waitcnt vmcnt(9)
	v_cndmask_b32_e32 v31, 0, v18, vcc
	ds_write_b32 v30, v31 offset:6240
	s_waitcnt vmcnt(8)
	v_cndmask_b32_e32 v32, 0, v19, vcc
	ds_write_b32 v30, v32 offset:7280
	s_waitcnt vmcnt(7)
	v_cndmask_b32_e32 v31, 0, v20, vcc
	ds_write_b32 v30, v31 offset:8320
	s_waitcnt vmcnt(6)
	v_cndmask_b32_e32 v32, 0, v21, vcc
	ds_write_b32 v30, v32 offset:9360
	s_waitcnt vmcnt(5)
	v_cndmask_b32_e32 v31, 0, v22, vcc
	ds_write_b32 v30, v31 offset:10400
	s_waitcnt vmcnt(4)
	v_cndmask_b32_e32 v32, 0, v23, vcc
	ds_write_b32 v30, v32 offset:11440
	s_waitcnt vmcnt(3)
	v_cndmask_b32_e32 v31, 0, v24, vcc
	ds_write_b32 v30, v31 offset:12480
	s_waitcnt vmcnt(2)
	v_cndmask_b32_e32 v32, 0, v25, vcc
	ds_write_b32 v30, v32 offset:13520
	s_waitcnt vmcnt(1)
	v_cndmask_b32_e32 v31, 0, v26, vcc
	ds_write_b32 v30, v31 offset:14560
	s_waitcnt vmcnt(0)
	v_cndmask_b32_e32 v32, 0, v27, vcc
	ds_write_b32 v30, v32 offset:15600
	v_add_u32_e32 v4, 0x100, v1
	v_lshlrev_b32_e32 v0, 3, v1
	v_and_b32_e32 v5, 56, v0
	v_mul_u32_u24_e32 v10, 0x104, v5
	v_lshl_add_u32 v6, v11, 2, v10
	s_waitcnt lgkmcnt(0)
	s_barrier
	ds_read2_b32 v[0:1], v6 offset1:65
	ds_read2_b32 v[2:3], v6 offset0:130 offset1:195
	v_add_u32_e32 v8, 0x400, v6
	ds_read2_b32 v[6:7], v8 offset0:4 offset1:69
	ds_read2_b32 v[8:9], v8 offset0:134 offset1:199
	v_lshlrev_b32_e32 v134, 1, v5
	s_waitcnt lgkmcnt(3)
	v_cvt_pk_bf16_f32 v0, v0, v1
	s_waitcnt lgkmcnt(2)
	v_cvt_pk_bf16_f32 v1, v2, v3
	s_waitcnt lgkmcnt(1)
	v_cvt_pk_bf16_f32 v2, v6, v7
	v_add_u32_e32 v6, s4, v11
	v_mad_i64_i32 v[6:7], s[8:9], s6, v6, 0
	v_lshl_add_u64 v[6:7], v[6:7], 1, s[10:11]
	s_lshl_b64 s[8:9], s[12:13], 1
	v_lshl_add_u64 v[6:7], v[6:7], 0, s[8:9]
	s_waitcnt lgkmcnt(0)
	v_cvt_pk_bf16_f32 v3, v8, v9
	v_lshl_add_u64 v[6:7], v[6:7], 0, v[134:135]
	v_ashrrev_i32_e32 v8, 3, v4
	global_store_dwordx4 v[6:7], v[0:3], off
	v_lshl_add_u32 v4, v8, 2, v10
	ds_read2_b32 v[0:1], v4 offset1:65
	ds_read2_b32 v[2:3], v4 offset0:130 offset1:195
	v_add_u32_e32 v6, 0x400, v4
	ds_read2_b32 v[4:5], v6 offset0:4 offset1:69
	ds_read2_b32 v[6:7], v6 offset0:134 offset1:199
	s_waitcnt lgkmcnt(3)
	v_cvt_pk_bf16_f32 v0, v0, v1
	s_waitcnt lgkmcnt(2)
	v_cvt_pk_bf16_f32 v1, v2, v3
	s_waitcnt lgkmcnt(1)
	v_cvt_pk_bf16_f32 v2, v4, v5
	v_add_u32_e32 v4, s4, v8
	v_mad_i64_i32 v[4:5], s[6:7], s6, v4, 0
	v_lshl_add_u64 v[4:5], v[4:5], 1, s[10:11]
	v_readlane_b32 s4, v230, 26
	v_lshl_add_u64 v[4:5], v[4:5], 0, s[8:9]
	s_add_i32 s14, s4, s14
	s_waitcnt lgkmcnt(0)
	v_cvt_pk_bf16_f32 v3, v6, v7
	v_lshl_add_u64 v[4:5], v[4:5], 0, v[134:135]
	s_cmp_ge_i32 s14, s89
	global_store_dwordx4 v[4:5], v[0:3], off
	s_cbranch_scc1 .LBB0_592
